# v32 + P3 chain epilogue: first three gate loads issued before the serialized first-load wait (one fewer memory round trip per n<3 epilogue)
# baseline (speedup 1.0000x reference)
.LBB0_499:
	s_lshl_b32 s0, s49, 8
	v_readlane_b32 s1, v254, 61
	v_mbcnt_lo_u32_b32 v130, -1, 0
	v_mbcnt_hi_u32_b32 v130, -1, v130
	s_add_i32 s0, s0, s1
	v_and_or_b32 v156, v130, 15, s0
	s_lshl_b32 s0, s48, 8
	v_ashrrev_i32_e32 v130, 1, v130
	v_and_b32_e32 v130, -8, v130
	s_or_b32 s0, s0, s81
	v_add_u32_e32 v154, s0, v130
	v_mov_b64_e32 v[130:131], s[10:11]
	v_mad_i64_i32 v[130:131], s[0:1], v156, s87, v[130:131]
	s_lshl_b32 s0, s47, 11
	s_ashr_i32 s1, s0, 31
	v_lshl_add_u64 v[130:131], s[0:1], 1, v[130:131]
	v_ashrrev_i32_e32 v155, 31, v154
	v_lshl_add_u64 v[134:135], v[154:155], 1, v[130:131]
	v_add_co_u32_e32 v130, vcc, 0x5000, v134
	s_cmp_gt_i32 s47, 2
	s_nop 0
	v_addc_co_u32_e32 v131, vcc, 0, v135, vcc
	global_load_dwordx4 v[130:133], v[130:131], off
	s_cselect_b64 s[26:27], -1, 0
	s_mov_b64 s[4:5], 0x5000
	s_mov_b64 s[0:1], -1
	s_and_b64 vcc, exec, s[26:27]
	v_lshl_add_u64 v[214:215], v[134:135], 0, s[4:5]
	s_cbranch_vccnz .Lh3_n3
	v_add_co_u32_e32 v220, vcc, 0x1000, v214
	s_nop 1
	v_addc_co_u32_e32 v221, vcc, 0, v215, vcc
	global_load_dwordx4 v[194:197], v[220:221], off
	global_load_dwordx4 v[178:181], v[214:215], off offset:256
	global_load_dwordx4 v[182:185], v[220:221], off offset:256
	s_mov_b64 vcc, 0
	s_waitcnt vmcnt(3)
	s_branch .Lh3_join

.Lh3_join:
	v_lshlrev_b32_e32 v192, 16, v130
	v_and_b32_e32 v193, 0xffff0000, v130
	v_lshlrev_b32_e32 v190, 16, v131
	v_and_b32_e32 v191, 0xffff0000, v131
	v_lshlrev_b32_e32 v188, 16, v132
	v_and_b32_e32 v189, 0xffff0000, v132
	v_lshlrev_b32_e32 v186, 16, v133
	v_and_b32_e32 v187, 0xffff0000, v133
	s_cbranch_vccnz .LBB0_502
	s_andn2_b64 vcc, exec, s[0:1]
	s_cbranch_vccz .LBB0_503

.LBB0_503:
	s_mov_b32 s0, 0x120000
	v_add_co_u32_e32 v130, vcc, 0x90000, v214
	s_waitcnt vmcnt(2)
	v_lshlrev_b32_e32 v198, 16, v194
	v_addc_co_u32_e32 v131, vcc, 0, v215, vcc
	global_load_dwordx4 v[170:173], v[130:131], off
	v_add_co_u32_e32 v132, vcc, 0x91000, v214
	v_and_b32_e32 v194, 0xffff0000, v194
	s_nop 0
	v_addc_co_u32_e32 v133, vcc, 0, v215, vcc
	global_load_dwordx4 v[174:177], v[132:133], off
	global_load_dwordx4 v[162:165], v[130:131], off offset:256
	global_load_dwordx4 v[166:169], v[132:133], off offset:256
	v_add_co_u32_e32 v130, vcc, s0, v214
	s_mov_b32 s0, 0x121000
	s_nop 0
	v_addc_co_u32_e32 v131, vcc, 0, v215, vcc
	v_add_co_u32_e32 v134, vcc, s0, v214
	v_rcp_f32_e32 v198, v198
	v_rcp_f32_e32 v199, v194
	v_addc_co_u32_e32 v135, vcc, 0, v215, vcc
	global_load_dwordx4 v[154:157], v[134:135], off offset:-4096
	global_load_dwordx4 v[158:161], v[134:135], off
	s_nop 0
	global_load_dwordx4 v[130:133], v[130:131], off offset:256
	s_nop 0
	global_load_dwordx4 v[138:141], v[134:135], off offset:256
	v_pk_mul_f32 v[192:193], v[198:199], v[192:193]
	s_mov_b32 s0, 0x1b0000
	v_pk_mul_f32 v[126:127], v[126:127], v[192:193]
	v_lshlrev_b32_e32 v192, 16, v195
	v_and_b32_e32 v193, 0xffff0000, v195
	v_rcp_f32_e32 v192, v192
	v_rcp_f32_e32 v193, v193
	v_add_co_u32_e32 v134, vcc, s0, v214
	s_mov_b32 s0, 0x1b1000
	v_pk_mul_f32 v[190:191], v[192:193], v[190:191]
	v_addc_co_u32_e32 v135, vcc, 0, v215, vcc
	v_pk_mul_f32 v[128:129], v[128:129], v[190:191]
	v_lshlrev_b32_e32 v190, 16, v196
	v_and_b32_e32 v191, 0xffff0000, v196
	v_rcp_f32_e32 v190, v190
	v_rcp_f32_e32 v191, v191
	v_add_co_u32_e32 v142, vcc, s0, v214
	s_mov_b32 s0, 0x480000
	v_pk_mul_f32 v[188:189], v[190:191], v[188:189]
	v_addc_co_u32_e32 v143, vcc, 0, v215, vcc
	v_pk_mul_f32 v[122:123], v[122:123], v[188:189]
	v_lshlrev_b32_e32 v188, 16, v197
	v_and_b32_e32 v189, 0xffff0000, v197
	v_rcp_f32_e32 v188, v188
	v_rcp_f32_e32 v189, v189
	global_load_dwordx4 v[146:149], v[142:143], off offset:-4096
	global_load_dwordx4 v[150:153], v[142:143], off
	s_nop 0
	global_load_dwordx4 v[134:137], v[134:135], off offset:256
	s_nop 0
	global_load_dwordx4 v[142:145], v[142:143], off offset:256
	v_pk_mul_f32 v[186:187], v[188:189], v[186:187]
	s_nop 0
	v_pk_mul_f32 v[124:125], v[124:125], v[186:187]
	s_waitcnt vmcnt(12)
	v_lshlrev_b32_e32 v186, 16, v182
	v_and_b32_e32 v182, 0xffff0000, v182
	v_lshlrev_b32_e32 v188, 16, v178
	v_and_b32_e32 v189, 0xffff0000, v178
	v_lshlrev_b32_e32 v178, 16, v183
	v_rcp_f32_e32 v187, v182
	v_rcp_f32_e32 v182, v178
	v_and_b32_e32 v178, 0xffff0000, v183
	v_rcp_f32_e32 v183, v178
	v_lshlrev_b32_e32 v178, 16, v179
	v_and_b32_e32 v179, 0xffff0000, v179
	v_rcp_f32_e32 v186, v186
	v_pk_mul_f32 v[178:179], v[182:183], v[178:179]
	v_lshlrev_b32_e32 v182, 16, v180
	v_pk_mul_f32 v[96:97], v[96:97], v[178:179]
	v_lshlrev_b32_e32 v178, 16, v184
	v_and_b32_e32 v179, 0xffff0000, v184
	v_rcp_f32_e32 v178, v178
	v_rcp_f32_e32 v179, v179
	v_and_b32_e32 v183, 0xffff0000, v180
	v_lshlrev_b32_e32 v180, 16, v181
	v_and_b32_e32 v181, 0xffff0000, v181
	v_pk_mul_f32 v[178:179], v[178:179], v[182:183]
	v_pk_mul_f32 v[186:187], v[186:187], v[188:189]
	v_pk_mul_f32 v[90:91], v[90:91], v[178:179]
	v_lshlrev_b32_e32 v178, 16, v185
	v_and_b32_e32 v179, 0xffff0000, v185
	v_rcp_f32_e32 v178, v178
	v_rcp_f32_e32 v179, v179
	v_pk_mul_f32 v[94:95], v[94:95], v[186:187]
	v_pk_mul_f32 v[178:179], v[178:179], v[180:181]
	s_nop 0
	v_pk_mul_f32 v[92:93], v[92:93], v[178:179]
	s_waitcnt vmcnt(10)
	v_lshlrev_b32_e32 v178, 16, v174
	v_and_b32_e32 v174, 0xffff0000, v174
	v_lshlrev_b32_e32 v180, 16, v170
	v_and_b32_e32 v181, 0xffff0000, v170
	v_lshlrev_b32_e32 v170, 16, v175
	v_rcp_f32_e32 v179, v174
	v_rcp_f32_e32 v174, v170
	v_and_b32_e32 v170, 0xffff0000, v175
	v_rcp_f32_e32 v175, v170
	v_lshlrev_b32_e32 v170, 16, v171
	v_and_b32_e32 v171, 0xffff0000, v171
	v_rcp_f32_e32 v178, v178
	v_pk_mul_f32 v[170:171], v[174:175], v[170:171]
	v_lshlrev_b32_e32 v174, 16, v172
	v_pk_mul_f32 v[120:121], v[120:121], v[170:171]
	v_lshlrev_b32_e32 v170, 16, v176
	v_and_b32_e32 v171, 0xffff0000, v176
	v_rcp_f32_e32 v170, v170
	v_rcp_f32_e32 v171, v171
	v_and_b32_e32 v175, 0xffff0000, v172
	v_lshlrev_b32_e32 v172, 16, v173
	v_and_b32_e32 v173, 0xffff0000, v173
	v_pk_mul_f32 v[170:171], v[170:171], v[174:175]
	v_pk_mul_f32 v[178:179], v[178:179], v[180:181]
	v_pk_mul_f32 v[114:115], v[114:115], v[170:171]
	v_lshlrev_b32_e32 v170, 16, v177
	v_and_b32_e32 v171, 0xffff0000, v177
	v_rcp_f32_e32 v170, v170
	v_rcp_f32_e32 v171, v171
	v_pk_mul_f32 v[118:119], v[118:119], v[178:179]
	v_pk_mul_f32 v[170:171], v[170:171], v[172:173]
	s_nop 0
	v_pk_mul_f32 v[116:117], v[116:117], v[170:171]
	s_waitcnt vmcnt(8)
	v_lshlrev_b32_e32 v170, 16, v166
	v_and_b32_e32 v166, 0xffff0000, v166
	v_lshlrev_b32_e32 v172, 16, v162
	v_and_b32_e32 v173, 0xffff0000, v162
	v_lshlrev_b32_e32 v162, 16, v167
	v_rcp_f32_e32 v171, v166
	v_rcp_f32_e32 v166, v162
	v_and_b32_e32 v162, 0xffff0000, v167
	v_rcp_f32_e32 v167, v162
	v_lshlrev_b32_e32 v162, 16, v163
	v_and_b32_e32 v163, 0xffff0000, v163
	v_rcp_f32_e32 v170, v170
	v_pk_mul_f32 v[162:163], v[166:167], v[162:163]
	v_lshlrev_b32_e32 v166, 16, v164
	v_pk_mul_f32 v[88:89], v[88:89], v[162:163]
	v_lshlrev_b32_e32 v162, 16, v168
	v_and_b32_e32 v163, 0xffff0000, v168
	v_rcp_f32_e32 v162, v162
	v_rcp_f32_e32 v163, v163
	v_and_b32_e32 v167, 0xffff0000, v164
	v_lshlrev_b32_e32 v164, 16, v165
	v_and_b32_e32 v165, 0xffff0000, v165
	v_pk_mul_f32 v[162:163], v[162:163], v[166:167]
	v_pk_mul_f32 v[170:171], v[170:171], v[172:173]
	v_pk_mul_f32 v[82:83], v[82:83], v[162:163]
	v_lshlrev_b32_e32 v162, 16, v169
	v_and_b32_e32 v163, 0xffff0000, v169
	v_rcp_f32_e32 v162, v162
	v_rcp_f32_e32 v163, v163
	v_pk_mul_f32 v[86:87], v[86:87], v[170:171]
	v_pk_mul_f32 v[162:163], v[162:163], v[164:165]
	s_nop 0
	v_pk_mul_f32 v[84:85], v[84:85], v[162:163]
	s_waitcnt vmcnt(6)
	v_lshlrev_b32_e32 v162, 16, v158
	v_and_b32_e32 v158, 0xffff0000, v158
	v_lshlrev_b32_e32 v164, 16, v154
	v_and_b32_e32 v165, 0xffff0000, v154
	v_lshlrev_b32_e32 v154, 16, v159
	v_rcp_f32_e32 v163, v158
	v_rcp_f32_e32 v158, v154
	v_and_b32_e32 v154, 0xffff0000, v159
	v_rcp_f32_e32 v159, v154
	v_lshlrev_b32_e32 v154, 16, v155
	v_and_b32_e32 v155, 0xffff0000, v155
	v_rcp_f32_e32 v162, v162
	v_pk_mul_f32 v[154:155], v[158:159], v[154:155]
	v_lshlrev_b32_e32 v158, 16, v156
	v_pk_mul_f32 v[112:113], v[112:113], v[154:155]
	v_lshlrev_b32_e32 v154, 16, v160
	v_and_b32_e32 v155, 0xffff0000, v160
	v_rcp_f32_e32 v154, v154
	v_rcp_f32_e32 v155, v155
	v_and_b32_e32 v159, 0xffff0000, v156
	v_lshlrev_b32_e32 v156, 16, v157
	v_and_b32_e32 v157, 0xffff0000, v157
	v_pk_mul_f32 v[154:155], v[154:155], v[158:159]
	v_pk_mul_f32 v[162:163], v[162:163], v[164:165]
	v_pk_mul_f32 v[106:107], v[106:107], v[154:155]
	v_lshlrev_b32_e32 v154, 16, v161
	v_and_b32_e32 v155, 0xffff0000, v161
	v_rcp_f32_e32 v154, v154
	v_rcp_f32_e32 v155, v155
	v_pk_mul_f32 v[110:111], v[110:111], v[162:163]
	v_pk_mul_f32 v[154:155], v[154:155], v[156:157]
	s_nop 0
	v_pk_mul_f32 v[108:109], v[108:109], v[154:155]
	s_waitcnt vmcnt(4)
	v_lshlrev_b32_e32 v154, 16, v138
	v_and_b32_e32 v138, 0xffff0000, v138
	v_lshlrev_b32_e32 v156, 16, v130
	v_and_b32_e32 v157, 0xffff0000, v130
	v_lshlrev_b32_e32 v130, 16, v139
	v_rcp_f32_e32 v155, v138
	v_rcp_f32_e32 v138, v130
	v_and_b32_e32 v130, 0xffff0000, v139
	v_rcp_f32_e32 v139, v130
	v_lshlrev_b32_e32 v130, 16, v131
	v_and_b32_e32 v131, 0xffff0000, v131
	v_rcp_f32_e32 v154, v154
	v_pk_mul_f32 v[130:131], v[138:139], v[130:131]
	v_lshlrev_b32_e32 v138, 16, v132
	v_pk_mul_f32 v[80:81], v[80:81], v[130:131]
	v_lshlrev_b32_e32 v130, 16, v140
	v_and_b32_e32 v131, 0xffff0000, v140
	v_rcp_f32_e32 v130, v130
	v_rcp_f32_e32 v131, v131
	v_and_b32_e32 v139, 0xffff0000, v132
	v_lshlrev_b32_e32 v132, 16, v133
	v_and_b32_e32 v133, 0xffff0000, v133
	v_pk_mul_f32 v[130:131], v[130:131], v[138:139]
	v_pk_mul_f32 v[154:155], v[154:155], v[156:157]
	v_pk_mul_f32 v[74:75], v[74:75], v[130:131]
	v_lshlrev_b32_e32 v130, 16, v141
	v_and_b32_e32 v131, 0xffff0000, v141
	v_rcp_f32_e32 v130, v130
	v_rcp_f32_e32 v131, v131
	v_pk_mul_f32 v[78:79], v[78:79], v[154:155]
	v_pk_mul_f32 v[130:131], v[130:131], v[132:133]
	s_nop 0
	v_pk_mul_f32 v[76:77], v[76:77], v[130:131]
	s_waitcnt vmcnt(2)
	v_lshlrev_b32_e32 v130, 16, v150
	v_and_b32_e32 v131, 0xffff0000, v150
	v_rcp_f32_e32 v130, v130
	v_rcp_f32_e32 v131, v131
	v_lshlrev_b32_e32 v132, 16, v146
	v_and_b32_e32 v133, 0xffff0000, v146
	v_pk_mul_f32 v[130:131], v[130:131], v[132:133]
	s_nop 0
	v_pk_mul_f32 v[102:103], v[102:103], v[130:131]
	v_lshlrev_b32_e32 v130, 16, v151
	v_and_b32_e32 v131, 0xffff0000, v151
	v_rcp_f32_e32 v130, v130
	v_rcp_f32_e32 v131, v131
	v_lshlrev_b32_e32 v132, 16, v147
	v_and_b32_e32 v133, 0xffff0000, v147
	v_pk_mul_f32 v[130:131], v[130:131], v[132:133]
	s_nop 0
	v_pk_mul_f32 v[104:105], v[104:105], v[130:131]
	v_lshlrev_b32_e32 v130, 16, v152
	v_and_b32_e32 v131, 0xffff0000, v152
	v_rcp_f32_e32 v130, v130
	v_rcp_f32_e32 v131, v131
	v_lshlrev_b32_e32 v132, 16, v148
	v_and_b32_e32 v133, 0xffff0000, v148
	v_pk_mul_f32 v[130:131], v[130:131], v[132:133]
	s_nop 0
	v_pk_mul_f32 v[98:99], v[98:99], v[130:131]
	v_lshlrev_b32_e32 v130, 16, v153
	v_and_b32_e32 v131, 0xffff0000, v153
	v_rcp_f32_e32 v130, v130
	v_rcp_f32_e32 v131, v131
	v_lshlrev_b32_e32 v132, 16, v149
	v_and_b32_e32 v133, 0xffff0000, v149
	v_pk_mul_f32 v[130:131], v[130:131], v[132:133]
	s_nop 0
	v_pk_mul_f32 v[100:101], v[100:101], v[130:131]
	s_waitcnt vmcnt(0)
	v_lshlrev_b32_e32 v130, 16, v142
	v_and_b32_e32 v131, 0xffff0000, v142
	v_rcp_f32_e32 v130, v130
	v_rcp_f32_e32 v131, v131
	v_lshlrev_b32_e32 v132, 16, v134
	v_and_b32_e32 v133, 0xffff0000, v134
	v_pk_mul_f32 v[130:131], v[130:131], v[132:133]
	s_nop 0
	v_pk_mul_f32 v[70:71], v[70:71], v[130:131]
	v_lshlrev_b32_e32 v130, 16, v143
	v_and_b32_e32 v131, 0xffff0000, v143
	v_rcp_f32_e32 v130, v130
	v_rcp_f32_e32 v131, v131
	v_lshlrev_b32_e32 v132, 16, v135
	v_and_b32_e32 v133, 0xffff0000, v135
	v_pk_mul_f32 v[130:131], v[130:131], v[132:133]
	s_nop 0
	v_pk_mul_f32 v[72:73], v[72:73], v[130:131]
	v_lshlrev_b32_e32 v130, 16, v144
	v_and_b32_e32 v131, 0xffff0000, v144
	v_rcp_f32_e32 v130, v130
	v_rcp_f32_e32 v131, v131
	v_lshlrev_b32_e32 v132, 16, v136
	v_and_b32_e32 v133, 0xffff0000, v136
	v_pk_mul_f32 v[130:131], v[130:131], v[132:133]
	s_nop 0
	v_pk_mul_f32 v[66:67], v[66:67], v[130:131]
	v_lshlrev_b32_e32 v130, 16, v145
	v_and_b32_e32 v131, 0xffff0000, v145
	v_rcp_f32_e32 v130, v130
	v_rcp_f32_e32 v131, v131
	v_lshlrev_b32_e32 v132, 16, v137
	v_and_b32_e32 v133, 0xffff0000, v137
	v_pk_mul_f32 v[130:131], v[130:131], v[132:133]
	s_nop 0
	v_pk_mul_f32 v[68:69], v[68:69], v[130:131]
	v_add_co_u32_e32 v130, vcc, s0, v214
	s_mov_b32 s0, 0x481000
	s_nop 0
	v_addc_co_u32_e32 v131, vcc, 0, v215, vcc
	v_add_co_u32_e32 v132, vcc, s0, v214
	s_mov_b32 s0, 0x510000
	s_nop 0
	v_addc_co_u32_e32 v133, vcc, 0, v215, vcc
	global_load_dwordx4 v[174:177], v[132:133], off offset:-4096
	global_load_dwordx4 v[178:181], v[132:133], off
	global_load_dwordx4 v[162:165], v[130:131], off offset:256
	global_load_dwordx4 v[190:193], v[132:133], off offset:256
	v_add_co_u32_e32 v130, vcc, s0, v214
	s_mov_b32 s0, 0x511000
	s_nop 0
	v_addc_co_u32_e32 v131, vcc, 0, v215, vcc
	v_add_co_u32_e32 v132, vcc, s0, v214
	s_mov_b32 s0, 0x5a0000
	s_nop 0
	v_addc_co_u32_e32 v133, vcc, 0, v215, vcc
	global_load_dwordx4 v[182:185], v[132:133], off offset:-4096
	global_load_dwordx4 v[186:189], v[132:133], off
	global_load_dwordx4 v[166:169], v[130:131], off offset:256
	global_load_dwordx4 v[170:173], v[132:133], off offset:256
	v_add_co_u32_e32 v130, vcc, s0, v214
	s_mov_b32 s0, 0x5a1000
	s_nop 0
	v_addc_co_u32_e32 v131, vcc, 0, v215, vcc
	v_add_co_u32_e32 v132, vcc, s0, v214
	s_mov_b32 s0, 0x630000
	s_nop 0
	v_addc_co_u32_e32 v133, vcc, 0, v215, vcc
	global_load_dwordx4 v[154:157], v[132:133], off offset:-4096
	global_load_dwordx4 v[158:161], v[132:133], off
	global_load_dwordx4 v[146:149], v[130:131], off offset:256
	global_load_dwordx4 v[150:153], v[132:133], off offset:256
	v_add_co_u32_e32 v130, vcc, s0, v214
	s_mov_b32 s0, 0x631000
	s_nop 0
	v_addc_co_u32_e32 v131, vcc, 0, v215, vcc
	v_add_co_u32_e32 v134, vcc, s0, v214
	s_waitcnt vmcnt(11)
	v_lshlrev_b32_e32 v196, 16, v174
	s_waitcnt vmcnt(10)
	v_lshlrev_b32_e32 v194, 16, v178
	v_and_b32_e32 v178, 0xffff0000, v178
	v_and_b32_e32 v197, 0xffff0000, v174
	v_lshlrev_b32_e32 v174, 16, v179
	v_rcp_f32_e32 v195, v178
	v_rcp_f32_e32 v178, v174
	v_and_b32_e32 v174, 0xffff0000, v179
	v_rcp_f32_e32 v179, v174
	v_lshlrev_b32_e32 v174, 16, v175
	v_and_b32_e32 v175, 0xffff0000, v175
	v_addc_co_u32_e32 v135, vcc, 0, v215, vcc
	v_pk_mul_f32 v[174:175], v[178:179], v[174:175]
	v_lshlrev_b32_e32 v178, 16, v176
	v_pk_mul_f32 v[64:65], v[64:65], v[174:175]
	v_lshlrev_b32_e32 v174, 16, v180
	v_and_b32_e32 v175, 0xffff0000, v180
	v_rcp_f32_e32 v174, v174
	v_rcp_f32_e32 v175, v175
	v_and_b32_e32 v179, 0xffff0000, v176
	v_lshlrev_b32_e32 v176, 16, v177
	v_and_b32_e32 v177, 0xffff0000, v177
	v_pk_mul_f32 v[174:175], v[174:175], v[178:179]
	global_load_dwordx4 v[138:141], v[134:135], off offset:-4096
	global_load_dwordx4 v[142:145], v[134:135], off
	s_nop 0
	global_load_dwordx4 v[130:133], v[130:131], off offset:256
	s_nop 0
	global_load_dwordx4 v[134:137], v[134:135], off offset:256
	v_pk_mul_f32 v[58:59], v[58:59], v[174:175]
	v_lshlrev_b32_e32 v174, 16, v181
	v_and_b32_e32 v175, 0xffff0000, v181
	v_rcp_f32_e32 v174, v174
	v_rcp_f32_e32 v175, v175
	v_rcp_f32_e32 v194, v194
	v_pk_mul_f32 v[174:175], v[174:175], v[176:177]
	s_nop 0
	v_pk_mul_f32 v[60:61], v[60:61], v[174:175]
	s_waitcnt vmcnt(12)
	v_lshlrev_b32_e32 v174, 16, v190
	v_and_b32_e32 v175, 0xffff0000, v190
	v_rcp_f32_e32 v174, v174
	v_rcp_f32_e32 v175, v175
	v_lshlrev_b32_e32 v176, 16, v162
	v_and_b32_e32 v177, 0xffff0000, v162
	v_lshlrev_b32_e32 v162, 16, v191
	v_pk_mul_f32 v[174:175], v[174:175], v[176:177]
	v_pk_mul_f32 v[194:195], v[194:195], v[196:197]
	v_pk_mul_f32 v[30:31], v[30:31], v[174:175]
	v_rcp_f32_e32 v174, v162
	v_and_b32_e32 v162, 0xffff0000, v191
	v_rcp_f32_e32 v175, v162
	v_lshlrev_b32_e32 v162, 16, v163
	v_and_b32_e32 v163, 0xffff0000, v163
	v_pk_mul_f32 v[62:63], v[62:63], v[194:195]
	v_pk_mul_f32 v[162:163], v[174:175], v[162:163]
	v_lshlrev_b32_e32 v174, 16, v164
	v_pk_mul_f32 v[32:33], v[32:33], v[162:163]
	v_lshlrev_b32_e32 v162, 16, v192
	v_and_b32_e32 v163, 0xffff0000, v192
	v_rcp_f32_e32 v162, v162
	v_rcp_f32_e32 v163, v163
	v_and_b32_e32 v175, 0xffff0000, v164
	v_lshlrev_b32_e32 v164, 16, v165
	v_and_b32_e32 v165, 0xffff0000, v165
	v_pk_mul_f32 v[162:163], v[162:163], v[174:175]
	s_nop 0
	v_pk_mul_f32 v[26:27], v[26:27], v[162:163]
	v_lshlrev_b32_e32 v162, 16, v193
	v_and_b32_e32 v163, 0xffff0000, v193
	v_rcp_f32_e32 v162, v162
	v_rcp_f32_e32 v163, v163
	s_nop 0
	v_pk_mul_f32 v[162:163], v[162:163], v[164:165]
	s_nop 0
	v_pk_mul_f32 v[28:29], v[28:29], v[162:163]
	s_waitcnt vmcnt(10)
	v_lshlrev_b32_e32 v162, 16, v186
	v_and_b32_e32 v163, 0xffff0000, v186
	v_rcp_f32_e32 v162, v162
	v_rcp_f32_e32 v163, v163
	v_lshlrev_b32_e32 v164, 16, v182
	v_and_b32_e32 v165, 0xffff0000, v182
	v_pk_mul_f32 v[162:163], v[162:163], v[164:165]
	s_nop 0
	v_pk_mul_f32 v[54:55], v[54:55], v[162:163]
	v_lshlrev_b32_e32 v162, 16, v187
	v_and_b32_e32 v163, 0xffff0000, v187
	v_rcp_f32_e32 v162, v162
	v_rcp_f32_e32 v163, v163
	v_lshlrev_b32_e32 v164, 16, v183
	v_and_b32_e32 v165, 0xffff0000, v183
	v_pk_mul_f32 v[162:163], v[162:163], v[164:165]
	s_nop 0
	v_pk_mul_f32 v[56:57], v[56:57], v[162:163]
	v_lshlrev_b32_e32 v162, 16, v188
	v_and_b32_e32 v163, 0xffff0000, v188
	v_rcp_f32_e32 v162, v162
	v_rcp_f32_e32 v163, v163
	v_lshlrev_b32_e32 v164, 16, v184
	v_and_b32_e32 v165, 0xffff0000, v184
	v_pk_mul_f32 v[162:163], v[162:163], v[164:165]
	s_nop 0
	v_pk_mul_f32 v[50:51], v[50:51], v[162:163]
	v_lshlrev_b32_e32 v162, 16, v189
	v_and_b32_e32 v163, 0xffff0000, v189
	v_rcp_f32_e32 v162, v162
	v_rcp_f32_e32 v163, v163
	v_lshlrev_b32_e32 v164, 16, v185
	v_and_b32_e32 v165, 0xffff0000, v185
	v_pk_mul_f32 v[162:163], v[162:163], v[164:165]
	s_nop 0
	v_pk_mul_f32 v[52:53], v[52:53], v[162:163]
	s_waitcnt vmcnt(8)
	v_lshlrev_b32_e32 v162, 16, v170
	v_and_b32_e32 v163, 0xffff0000, v170
	v_rcp_f32_e32 v162, v162
	v_rcp_f32_e32 v163, v163
	v_lshlrev_b32_e32 v164, 16, v166
	v_and_b32_e32 v165, 0xffff0000, v166
	v_pk_mul_f32 v[162:163], v[162:163], v[164:165]
	s_nop 0
	v_pk_mul_f32 v[22:23], v[22:23], v[162:163]
	v_lshlrev_b32_e32 v162, 16, v171
	v_and_b32_e32 v163, 0xffff0000, v171
	v_rcp_f32_e32 v162, v162
	v_rcp_f32_e32 v163, v163
	v_lshlrev_b32_e32 v164, 16, v167
	v_and_b32_e32 v165, 0xffff0000, v167
	v_pk_mul_f32 v[162:163], v[162:163], v[164:165]
	s_nop 0
	v_pk_mul_f32 v[24:25], v[24:25], v[162:163]
	v_lshlrev_b32_e32 v162, 16, v172
	v_and_b32_e32 v163, 0xffff0000, v172
	v_rcp_f32_e32 v162, v162
	v_rcp_f32_e32 v163, v163
	v_lshlrev_b32_e32 v164, 16, v168
	v_and_b32_e32 v165, 0xffff0000, v168
	v_pk_mul_f32 v[162:163], v[162:163], v[164:165]
	s_nop 0
	v_pk_mul_f32 v[18:19], v[18:19], v[162:163]
	v_lshlrev_b32_e32 v162, 16, v173
	v_and_b32_e32 v163, 0xffff0000, v173
	v_rcp_f32_e32 v162, v162
	v_rcp_f32_e32 v163, v163
	v_lshlrev_b32_e32 v164, 16, v169
	v_and_b32_e32 v165, 0xffff0000, v169
	v_pk_mul_f32 v[162:163], v[162:163], v[164:165]
	s_nop 0
	v_pk_mul_f32 v[20:21], v[20:21], v[162:163]
	s_waitcnt vmcnt(6)
	v_lshlrev_b32_e32 v162, 16, v158
	v_and_b32_e32 v158, 0xffff0000, v158
	v_lshlrev_b32_e32 v164, 16, v154
	v_and_b32_e32 v165, 0xffff0000, v154
	v_lshlrev_b32_e32 v154, 16, v159
	v_rcp_f32_e32 v163, v158
	v_rcp_f32_e32 v158, v154
	v_and_b32_e32 v154, 0xffff0000, v159
	v_rcp_f32_e32 v159, v154
	v_lshlrev_b32_e32 v154, 16, v155
	v_and_b32_e32 v155, 0xffff0000, v155
	v_rcp_f32_e32 v162, v162
	v_pk_mul_f32 v[154:155], v[158:159], v[154:155]
	v_lshlrev_b32_e32 v158, 16, v156
	v_pk_mul_f32 v[48:49], v[48:49], v[154:155]
	v_lshlrev_b32_e32 v154, 16, v160
	v_and_b32_e32 v155, 0xffff0000, v160
	v_rcp_f32_e32 v154, v154
	v_rcp_f32_e32 v155, v155
	v_and_b32_e32 v159, 0xffff0000, v156
	v_lshlrev_b32_e32 v156, 16, v157
	v_and_b32_e32 v157, 0xffff0000, v157
	v_pk_mul_f32 v[154:155], v[154:155], v[158:159]
	v_pk_mul_f32 v[162:163], v[162:163], v[164:165]
	v_pk_mul_f32 v[42:43], v[42:43], v[154:155]
	v_lshlrev_b32_e32 v154, 16, v161
	v_and_b32_e32 v155, 0xffff0000, v161
	v_rcp_f32_e32 v154, v154
	v_rcp_f32_e32 v155, v155
	v_pk_mul_f32 v[46:47], v[46:47], v[162:163]
	v_pk_mul_f32 v[154:155], v[154:155], v[156:157]
	s_nop 0
	v_pk_mul_f32 v[44:45], v[44:45], v[154:155]
	s_waitcnt vmcnt(4)
	v_lshlrev_b32_e32 v154, 16, v150
	v_and_b32_e32 v150, 0xffff0000, v150
	v_lshlrev_b32_e32 v156, 16, v146
	v_and_b32_e32 v157, 0xffff0000, v146
	v_lshlrev_b32_e32 v146, 16, v151
	v_rcp_f32_e32 v155, v150
	v_rcp_f32_e32 v150, v146
	v_and_b32_e32 v146, 0xffff0000, v151
	v_rcp_f32_e32 v151, v146
	v_lshlrev_b32_e32 v146, 16, v147
	v_and_b32_e32 v147, 0xffff0000, v147
	v_rcp_f32_e32 v154, v154
	v_pk_mul_f32 v[146:147], v[150:151], v[146:147]
	v_lshlrev_b32_e32 v150, 16, v148
	v_pk_mul_f32 v[16:17], v[16:17], v[146:147]
	v_lshlrev_b32_e32 v146, 16, v152
	v_and_b32_e32 v147, 0xffff0000, v152
	v_rcp_f32_e32 v146, v146
	v_rcp_f32_e32 v147, v147
	v_and_b32_e32 v151, 0xffff0000, v148
	v_lshlrev_b32_e32 v148, 16, v149
	v_and_b32_e32 v149, 0xffff0000, v149
	v_pk_mul_f32 v[146:147], v[146:147], v[150:151]
	v_pk_mul_f32 v[154:155], v[154:155], v[156:157]
	v_pk_mul_f32 v[10:11], v[10:11], v[146:147]
	v_lshlrev_b32_e32 v146, 16, v153
	v_and_b32_e32 v147, 0xffff0000, v153
	v_rcp_f32_e32 v146, v146
	v_rcp_f32_e32 v147, v147
	v_pk_mul_f32 v[14:15], v[14:15], v[154:155]
	v_pk_mul_f32 v[146:147], v[146:147], v[148:149]
	s_nop 0
	v_pk_mul_f32 v[12:13], v[12:13], v[146:147]
	s_waitcnt vmcnt(2)
	v_lshlrev_b32_e32 v146, 16, v142
	v_and_b32_e32 v142, 0xffff0000, v142
	v_lshlrev_b32_e32 v148, 16, v138
	v_and_b32_e32 v149, 0xffff0000, v138
	v_lshlrev_b32_e32 v138, 16, v143
	v_rcp_f32_e32 v147, v142
	v_rcp_f32_e32 v142, v138
	v_and_b32_e32 v138, 0xffff0000, v143
	v_rcp_f32_e32 v143, v138
	v_lshlrev_b32_e32 v138, 16, v139
	v_and_b32_e32 v139, 0xffff0000, v139
	v_rcp_f32_e32 v146, v146
	v_pk_mul_f32 v[138:139], v[142:143], v[138:139]
	v_lshlrev_b32_e32 v142, 16, v140
	v_pk_mul_f32 v[40:41], v[40:41], v[138:139]
	v_lshlrev_b32_e32 v138, 16, v144
	v_and_b32_e32 v139, 0xffff0000, v144
	v_rcp_f32_e32 v138, v138
	v_rcp_f32_e32 v139, v139
	v_and_b32_e32 v143, 0xffff0000, v140
	v_lshlrev_b32_e32 v140, 16, v141
	v_and_b32_e32 v141, 0xffff0000, v141
	v_pk_mul_f32 v[138:139], v[138:139], v[142:143]
	v_pk_mul_f32 v[146:147], v[146:147], v[148:149]
	v_pk_mul_f32 v[34:35], v[34:35], v[138:139]
	v_lshlrev_b32_e32 v138, 16, v145
	v_and_b32_e32 v139, 0xffff0000, v145
	v_rcp_f32_e32 v138, v138
	v_rcp_f32_e32 v139, v139
	v_pk_mul_f32 v[38:39], v[38:39], v[146:147]
	v_pk_mul_f32 v[138:139], v[138:139], v[140:141]
	s_nop 0
	v_pk_mul_f32 v[36:37], v[36:37], v[138:139]
	s_waitcnt vmcnt(0)
	v_lshlrev_b32_e32 v138, 16, v134
	v_and_b32_e32 v134, 0xffff0000, v134
	v_lshlrev_b32_e32 v140, 16, v130
	v_and_b32_e32 v141, 0xffff0000, v130
	v_lshlrev_b32_e32 v130, 16, v135
	v_rcp_f32_e32 v139, v134
	v_rcp_f32_e32 v134, v130
	v_and_b32_e32 v130, 0xffff0000, v135
	v_rcp_f32_e32 v135, v130
	v_lshlrev_b32_e32 v130, 16, v131
	v_and_b32_e32 v131, 0xffff0000, v131
	v_rcp_f32_e32 v138, v138
	v_pk_mul_f32 v[130:131], v[134:135], v[130:131]
	v_lshlrev_b32_e32 v134, 16, v132
	v_pk_mul_f32 v[8:9], v[8:9], v[130:131]
	v_lshlrev_b32_e32 v130, 16, v136
	v_and_b32_e32 v131, 0xffff0000, v136
	v_rcp_f32_e32 v130, v130
	v_rcp_f32_e32 v131, v131
	v_and_b32_e32 v135, 0xffff0000, v132
	v_lshlrev_b32_e32 v132, 16, v133
	v_and_b32_e32 v133, 0xffff0000, v133
	v_pk_mul_f32 v[130:131], v[130:131], v[134:135]
	v_pk_mul_f32 v[138:139], v[138:139], v[140:141]
	v_pk_mul_f32 v[2:3], v[2:3], v[130:131]
	v_lshlrev_b32_e32 v130, 16, v137
	v_and_b32_e32 v131, 0xffff0000, v137
	v_rcp_f32_e32 v130, v130
	v_rcp_f32_e32 v131, v131
	v_pk_mul_f32 v[6:7], v[6:7], v[138:139]
	v_pk_mul_f32 v[130:131], v[130:131], v[132:133]
	s_nop 0
	v_pk_mul_f32 v[4:5], v[4:5], v[130:131]
	s_andn2_b64 vcc, exec, s[8:9]
	s_mov_b64 s[0:1], -1
	s_cbranch_vccnz .LBB0_488
